# v54 + one static s_setprio 1 for waves 0-3 at each attention unit entry
# speedup vs baseline: 1.0007x; 1.0007x over previous
; __device__ void mixer_phase(const Params& P, int l, unsigned char* smem) {
;     ...
;     for (;;) {
;         __syncthreads();
;         if (tid0 == 0) slot[0] = atomicAdd(ctr, 1u);
;         __syncthreads();
;         const unsigned u = slot[0];
.LBB0_141:
	s_barrier
	v_readfirstlane_b32 s0, v154
	s_nop 3
	s_cmp_lt_u32 s0, 0x100
	s_cbranch_scc0 .Latt_noprio
	s_setprio 1
